# norm_rows (both instances): the 24 per-row g/scale/shift vector loads issued together with counted waits
# speedup vs baseline: 1.0884x; 1.0005x over previous
; __device__ __forceinline__ unsigned pk2(float lo, float hi) { f32x2n v = {lo, hi}; bf16x2n b = __builtin_convertvector(v, bf16x2n); return __builtin_bit_cast(unsigned, b); }
; #define p (kparams())
; __device__ __forceinline__ void norm_rows(const int wv_, KPR p, int l, int src_layer, const float* gvec, int part_shift, int part_scale, bool copy_ctx) {
;     ...
;     const float rstd = rsqrtf(wave_sum(ss) * (1.f / D) + 1e-6f);
;     if (copy_ctx && row_who(row) == 4) { float* xd = xrow_dst(p, row);
; #pragma unroll
;       for (int j = 0; j < 8; ++j) *(f32x4*)(xd + lane * 4 + 256 * j) = v[j]; }
; #pragma unroll
;     for (int j = 0; j < 8; ++j) { const int c = lane * 4 + 256 * j;
;       const f32x4 g = *(const f32x4*)(gvec + c), sh = *(const f32x4*)(mw + part_shift * 2048 + c), sc = *(const f32x4*)(mw + part_scale * 2048 + c);
;       f32x4 o;
; #pragma unroll
;       for (int e = 0; e < 4; ++e) o[e] = v[j][e] * rstd * g[e] * (1.f + sc[e]) + sh[e];
;       u32x2 w; w.x = pk2(o[0], o[1]); w.y = pk2(o[2], o[3]);
;       *(u32x2*)(H + (size_t)row * D + c) = w; }
.LBB0_131:
	s_or_b64 exec, exec, s[20:21]
	v_mul_hi_i32_i24_e32 v65, 0xc000, v3
	v_mul_i32_i24_e32 v64, 0xc000, v3
	v_lshl_add_u64 v[64:65], s[14:15], 0, v[64:65]
	s_mov_b64 s[4:5], 0x2000
	v_lshl_add_u64 v[68:69], v[64:65], 0, s[4:5]
	v_mov_b32_e32 v67, v2
	v_lshl_add_u64 v[70:71], v[68:69], 0, v[66:67]
	v_lshl_add_u64 v[84:85], v[64:65], 0, v[66:67]
	s_mov_b64 s[4:5], 0x1000
	v_lshl_add_u64 v[222:223], v[38:39], 0, s[4:5]
	v_lshl_add_u64 v[224:225], v[70:71], 0, s[4:5]
	v_lshl_add_u64 v[226:227], v[84:85], 0, s[4:5]
	global_load_dwordx4 v[88:91], v[38:39], off
	global_load_dwordx4 v[120:123], v[70:71], off
	global_load_dwordx4 v[190:193], v[84:85], off
	global_load_dwordx4 v[92:95], v[38:39], off offset:1024
	global_load_dwordx4 v[124:127], v[70:71], off offset:1024
	global_load_dwordx4 v[194:197], v[84:85], off offset:1024
	global_load_dwordx4 v[96:99], v[38:39], off offset:2048
	global_load_dwordx4 v[128:131], v[70:71], off offset:2048
	global_load_dwordx4 v[198:201], v[84:85], off offset:2048
	global_load_dwordx4 v[100:103], v[38:39], off offset:3072
	global_load_dwordx4 v[132:135], v[70:71], off offset:3072
	global_load_dwordx4 v[202:205], v[84:85], off offset:3072
	global_load_dwordx4 v[104:107], v[222:223], off
	global_load_dwordx4 v[136:139], v[224:225], off
	global_load_dwordx4 v[206:209], v[226:227], off
	global_load_dwordx4 v[108:111], v[222:223], off offset:1024
	global_load_dwordx4 v[140:143], v[224:225], off offset:1024
	global_load_dwordx4 v[210:213], v[226:227], off offset:1024
	global_load_dwordx4 v[112:115], v[222:223], off offset:2048
	global_load_dwordx4 v[144:147], v[224:225], off offset:2048
	global_load_dwordx4 v[214:217], v[226:227], off offset:2048
	global_load_dwordx4 v[116:119], v[222:223], off offset:3072
	global_load_dwordx4 v[148:151], v[224:225], off offset:3072
	global_load_dwordx4 v[218:221], v[226:227], off offset:3072
	s_waitcnt lgkmcnt(0)
	v_add_f32_e32 v3, v53, v55
	v_fmamk_f32 v3, v3, 0x3a000000, v152
	v_mul_f32_e32 v37, 0x4b800000, v3
	v_cmp_gt_f32_e32 vcc, s96, v3
	v_ashrrev_i32_e32 v1, 31, v0
	v_lshlrev_b64 v[66:67], 12, v[0:1]
	v_cndmask_b32_e32 v3, v3, v37, vcc
	v_rsq_f32_e32 v3, v3
	v_lshl_add_u64 v[66:67], v[48:49], 0, v[66:67]
	v_mul_f32_e32 v1, 0x45800000, v3
	v_cndmask_b32_e32 v70, v3, v1, vcc
	v_pk_mul_f32 v[32:33], v[32:33], v[70:71] op_sel_hi:[1,0]
	v_pk_mul_f32 v[34:35], v[34:35], v[70:71] op_sel_hi:[1,0]
	v_pk_mul_f32 v[28:29], v[28:29], v[70:71] op_sel_hi:[1,0]
	v_pk_mul_f32 v[30:31], v[30:31], v[70:71] op_sel_hi:[1,0]
	v_pk_mul_f32 v[24:25], v[24:25], v[70:71] op_sel_hi:[1,0]
	v_pk_mul_f32 v[26:27], v[26:27], v[70:71] op_sel_hi:[1,0]
	v_pk_mul_f32 v[20:21], v[20:21], v[70:71] op_sel_hi:[1,0]
	v_pk_mul_f32 v[22:23], v[22:23], v[70:71] op_sel_hi:[1,0]
	v_pk_mul_f32 v[16:17], v[16:17], v[70:71] op_sel_hi:[1,0]
	v_pk_mul_f32 v[18:19], v[18:19], v[70:71] op_sel_hi:[1,0]
	v_pk_mul_f32 v[12:13], v[12:13], v[70:71] op_sel_hi:[1,0]
	v_pk_mul_f32 v[14:15], v[14:15], v[70:71] op_sel_hi:[1,0]
	v_pk_mul_f32 v[8:9], v[8:9], v[70:71] op_sel_hi:[1,0]
	v_pk_mul_f32 v[10:11], v[10:11], v[70:71] op_sel_hi:[1,0]
	v_pk_mul_f32 v[4:5], v[4:5], v[70:71] op_sel_hi:[1,0]
	v_pk_mul_f32 v[6:7], v[6:7], v[70:71] op_sel_hi:[1,0]
	v_add_u32_e32 v0, s73, v0
	v_cmp_lt_i32_e32 vcc, s35, v0
	s_or_b64 s[18:19], vcc, s[18:19]
	s_waitcnt vmcnt(21)
	v_pk_mul_f32 v[32:33], v[32:33], v[88:89]
	v_pk_mul_f32 v[34:35], v[34:35], v[90:91]
	v_pk_add_f32 v[228:229], v[120:121], 1.0 op_sel_hi:[1,0]
	v_pk_add_f32 v[230:231], v[122:123], 1.0 op_sel_hi:[1,0]
	v_pk_fma_f32 v[32:33], v[32:33], v[228:229], v[190:191]
	v_pk_fma_f32 v[34:35], v[34:35], v[230:231], v[192:193]
	v_cvt_pk_bf16_f32 v32, v32, v33
	v_cvt_pk_bf16_f32 v33, v34, v35
	global_store_dwordx2 v[66:67], v[32:33], off
	s_waitcnt vmcnt(19)
	v_pk_mul_f32 v[28:29], v[28:29], v[92:93]
	v_pk_mul_f32 v[30:31], v[30:31], v[94:95]
	v_pk_add_f32 v[228:229], v[124:125], 1.0 op_sel_hi:[1,0]
	v_pk_add_f32 v[230:231], v[126:127], 1.0 op_sel_hi:[1,0]
	v_pk_fma_f32 v[28:29], v[28:29], v[228:229], v[194:195]
	v_pk_fma_f32 v[30:31], v[30:31], v[230:231], v[196:197]
	v_cvt_pk_bf16_f32 v28, v28, v29
	v_cvt_pk_bf16_f32 v29, v30, v31
	global_store_dwordx2 v[66:67], v[28:29], off offset:512
	s_waitcnt vmcnt(17)
	v_pk_mul_f32 v[24:25], v[24:25], v[96:97]
	v_pk_mul_f32 v[26:27], v[26:27], v[98:99]
	v_pk_add_f32 v[228:229], v[128:129], 1.0 op_sel_hi:[1,0]
	v_pk_add_f32 v[230:231], v[130:131], 1.0 op_sel_hi:[1,0]
	v_pk_fma_f32 v[24:25], v[24:25], v[228:229], v[198:199]
	v_pk_fma_f32 v[26:27], v[26:27], v[230:231], v[200:201]
	v_cvt_pk_bf16_f32 v24, v24, v25
	v_cvt_pk_bf16_f32 v25, v26, v27
	global_store_dwordx2 v[66:67], v[24:25], off offset:1024
	s_waitcnt vmcnt(15)
	v_pk_mul_f32 v[20:21], v[20:21], v[100:101]
	v_pk_mul_f32 v[22:23], v[22:23], v[102:103]
	v_pk_add_f32 v[228:229], v[132:133], 1.0 op_sel_hi:[1,0]
	v_pk_add_f32 v[230:231], v[134:135], 1.0 op_sel_hi:[1,0]
	v_pk_fma_f32 v[20:21], v[20:21], v[228:229], v[202:203]
	v_pk_fma_f32 v[22:23], v[22:23], v[230:231], v[204:205]
	v_cvt_pk_bf16_f32 v20, v20, v21
	v_cvt_pk_bf16_f32 v21, v22, v23
	global_store_dwordx2 v[66:67], v[20:21], off offset:1536
	s_waitcnt vmcnt(13)
	v_pk_mul_f32 v[16:17], v[16:17], v[104:105]
	v_pk_mul_f32 v[18:19], v[18:19], v[106:107]
	v_pk_add_f32 v[228:229], v[136:137], 1.0 op_sel_hi:[1,0]
	v_pk_add_f32 v[230:231], v[138:139], 1.0 op_sel_hi:[1,0]
	v_pk_fma_f32 v[16:17], v[16:17], v[228:229], v[206:207]
	v_pk_fma_f32 v[18:19], v[18:19], v[230:231], v[208:209]
	v_cvt_pk_bf16_f32 v16, v16, v17
	v_cvt_pk_bf16_f32 v17, v18, v19
	global_store_dwordx2 v[66:67], v[16:17], off offset:2048
	s_waitcnt vmcnt(11)
	v_pk_mul_f32 v[12:13], v[12:13], v[108:109]
	v_pk_mul_f32 v[14:15], v[14:15], v[110:111]
	v_pk_add_f32 v[228:229], v[140:141], 1.0 op_sel_hi:[1,0]
	v_pk_add_f32 v[230:231], v[142:143], 1.0 op_sel_hi:[1,0]
	v_pk_fma_f32 v[12:13], v[12:13], v[228:229], v[210:211]
	v_pk_fma_f32 v[14:15], v[14:15], v[230:231], v[212:213]
	v_cvt_pk_bf16_f32 v12, v12, v13
	v_cvt_pk_bf16_f32 v13, v14, v15
	global_store_dwordx2 v[66:67], v[12:13], off offset:2560
	s_waitcnt vmcnt(9)
	v_pk_mul_f32 v[8:9], v[8:9], v[112:113]
	v_pk_mul_f32 v[10:11], v[10:11], v[114:115]
	v_pk_add_f32 v[228:229], v[144:145], 1.0 op_sel_hi:[1,0]
	v_pk_add_f32 v[230:231], v[146:147], 1.0 op_sel_hi:[1,0]
	v_pk_fma_f32 v[8:9], v[8:9], v[228:229], v[214:215]
	v_pk_fma_f32 v[10:11], v[10:11], v[230:231], v[216:217]
	v_cvt_pk_bf16_f32 v8, v8, v9
	v_cvt_pk_bf16_f32 v9, v10, v11
	global_store_dwordx2 v[66:67], v[8:9], off offset:3072
	s_waitcnt vmcnt(7)
	v_pk_mul_f32 v[4:5], v[4:5], v[116:117]
	v_pk_mul_f32 v[6:7], v[6:7], v[118:119]
	v_pk_add_f32 v[228:229], v[148:149], 1.0 op_sel_hi:[1,0]
	v_pk_add_f32 v[230:231], v[150:151], 1.0 op_sel_hi:[1,0]
	v_pk_fma_f32 v[4:5], v[4:5], v[228:229], v[218:219]
	v_pk_fma_f32 v[6:7], v[6:7], v[230:231], v[220:221]
	v_cvt_pk_bf16_f32 v4, v4, v5
	v_cvt_pk_bf16_f32 v5, v6, v7
	global_store_dwordx2 v[66:67], v[4:5], off offset:3584
	s_andn2_b64 exec, exec, s[18:19]
	s_cbranch_execz .LBB0_143

; #define p (kparams())
; __device__ __forceinline__ float wave_sum(float v) {
; #pragma unroll
;   for (int o = 1; o < 64; o <<= 1) v += __shfl_xor(v, o);
;   return v;
; }
; __device__ __forceinline__ void norm_rows(const int wv_, KPR p, int l, int src_layer, const float* gvec, int part_shift, int part_scale, bool copy_ctx) {
;     ...
;   for (int row = blockIdx.x * 8 + wid; row < T; row += gridDim.x * 8) {
;     const float* x = xrow_ptr(p, src_layer, row);
;     const float* mw = modl + (size_t)row_who(row) * 12288;
;     f32x4 v[8]; float ss = 0.f;
; #pragma unroll
;     for (int j = 0; j < 8; ++j) { v[j] = *(const f32x4*)(x + lane * 4 + 256 * j); ss += v[j][0] * v[j][0] + v[j][1] * v[j][1] + v[j][2] * v[j][2] + v[j][3] * v[j][3]; }
;     const float rstd = rsqrtf(wave_sum(ss) * (1.f / D) + 1e-6f);
;     if (copy_ctx && row_who(row) == 4) { float* xd = xrow_dst(p, row);
; #pragma unroll
;       for (int j = 0; j < 8; ++j) *(f32x4*)(xd + lane * 4 + 256 * j) = v[j]; }
; #pragma unroll
;     for (int j = 0; j < 8; ++j) { const int c = lane * 4 + 256 * j;
;       const f32x4 g = *(const f32x4*)(gvec + c), sh = *(const f32x4*)(mw + part_shift * 2048 + c), sc = *(const f32x4*)(mw + part_scale * 2048 + c);
.LBB0_1103:
	s_or_b64 exec, exec, s[20:21]
	v_ashrrev_i32_e32 v5, 31, v4
	v_lshlrev_b64 v[4:5], 13, v[4:5]
	v_lshl_add_u64 v[4:5], v[6:7], 0, v[4:5]
	v_mov_b32_e32 v49, v2
	v_lshl_add_u64 v[4:5], v[4:5], 0, v[48:49]
	global_load_dwordx4 v[32:35], v[4:5], off
	global_load_dwordx4 v[28:31], v[4:5], off offset:1024
	global_load_dwordx4 v[24:27], v[4:5], off offset:2048
	global_load_dwordx4 v[20:23], v[4:5], off offset:3072
	v_add_co_u32_e32 v4, vcc, s52, v4
	s_mov_b64 s[20:21], 0x6000
	s_nop 0
	v_addc_co_u32_e32 v5, vcc, 0, v5, vcc
	global_load_dwordx4 v[16:19], v[4:5], off
	global_load_dwordx4 v[12:15], v[4:5], off offset:1024
	v_mov_b32_e32 v51, v2
	v_mov_b32_e32 v53, v2
	v_mov_b32_e32 v55, v2
	v_mov_b32_e32 v57, v2
	v_mov_b32_e32 v59, v2
	v_mov_b32_e32 v61, v2
	v_mov_b32_e32 v63, v2
	s_waitcnt vmcnt(5)
	v_mul_f32_e32 v1, v33, v33
	s_waitcnt vmcnt(4)
	v_mul_f32_e32 v3, v29, v29
	v_fmac_f32_e32 v1, v32, v32
	v_fmac_f32_e32 v3, v28, v28
	v_fmac_f32_e32 v1, v34, v34
	v_fmac_f32_e32 v3, v30, v30
	v_fmac_f32_e32 v1, v35, v35
	v_fmac_f32_e32 v3, v31, v31
	v_add_f32_e32 v1, v1, v3
	s_waitcnt vmcnt(3)
	v_mul_f32_e32 v3, v25, v25
	v_fmac_f32_e32 v3, v24, v24
	v_fmac_f32_e32 v3, v26, v26
	v_fmac_f32_e32 v3, v27, v27
	v_add_f32_e32 v1, v1, v3
	s_waitcnt vmcnt(2)
	v_mul_f32_e32 v3, v21, v21
	s_waitcnt vmcnt(1)
	v_mov_b32_e32 v8, v17
	s_waitcnt vmcnt(0)
	v_mov_b32_e32 v9, v13
	v_fmac_f32_e32 v3, v20, v20
	v_mov_b32_e32 v6, v16
	v_mov_b32_e32 v7, v12
	v_pk_mul_f32 v[8:9], v[8:9], v[8:9]
	v_fmac_f32_e32 v3, v22, v22
	v_pk_fma_f32 v[6:7], v[6:7], v[6:7], v[8:9]
	v_mov_b32_e32 v8, v18
	v_mov_b32_e32 v9, v14
	v_fmac_f32_e32 v3, v23, v23
	v_pk_fma_f32 v[6:7], v[8:9], v[8:9], v[6:7]
	v_mov_b32_e32 v8, v19
	v_mov_b32_e32 v9, v15
	v_add_f32_e32 v1, v1, v3
	v_pk_fma_f32 v[6:7], v[8:9], v[8:9], v[6:7]
	s_nop 0
	v_add_f32_e32 v1, v1, v6
	v_add_f32_e32 v1, v1, v7
	global_load_dwordx4 v[8:11], v[4:5], off offset:2048
	s_nop 0
	global_load_dwordx4 v[4:7], v[4:5], off offset:3072
	s_waitcnt vmcnt(1)
	v_mov_b32_e32 v68, v9
	s_waitcnt vmcnt(0)
	v_mov_b32_e32 v69, v5
	v_mov_b32_e32 v66, v8
	v_mov_b32_e32 v67, v4
	v_pk_mul_f32 v[68:69], v[68:69], v[68:69]
	v_pk_fma_f32 v[66:67], v[66:67], v[66:67], v[68:69]
	v_mov_b32_e32 v68, v10
	v_mov_b32_e32 v69, v6
	v_pk_fma_f32 v[66:67], v[68:69], v[68:69], v[66:67]
	v_mov_b32_e32 v68, v11
	v_mov_b32_e32 v69, v7
	v_pk_fma_f32 v[66:67], v[68:69], v[68:69], v[66:67]
	s_nop 0
	v_add_f32_e32 v1, v1, v66
	v_add_f32_e32 v1, v1, v67
	v_lshl_add_u64 v[66:67], s[12:13], 0, v[64:65]
	v_lshl_add_u64 v[68:69], v[66:67], 0, s[20:21]
	s_mov_b64 s[20:21], 0x8000
	v_lshl_add_u64 v[66:67], v[66:67], 0, s[20:21]
	v_lshl_add_u64 v[74:75], v[68:69], 0, v[48:49]
	v_lshl_add_u64 v[78:79], v[66:67], 0, v[48:49]
	s_mov_b64 s[22:23], 0x1000
	v_lshl_add_u64 v[222:223], v[36:37], 0, s[22:23]
	v_lshl_add_u64 v[224:225], v[78:79], 0, s[22:23]
	v_lshl_add_u64 v[226:227], v[74:75], 0, s[22:23]
	global_load_dwordx4 v[88:91], v[36:37], off
	global_load_dwordx4 v[120:123], v[78:79], off
	global_load_dwordx4 v[190:193], v[74:75], off
	global_load_dwordx4 v[92:95], v[36:37], off offset:1024
	global_load_dwordx4 v[124:127], v[78:79], off offset:1024
	global_load_dwordx4 v[194:197], v[74:75], off offset:1024
	global_load_dwordx4 v[96:99], v[36:37], off offset:2048
	global_load_dwordx4 v[128:131], v[78:79], off offset:2048
	global_load_dwordx4 v[198:201], v[74:75], off offset:2048
	global_load_dwordx4 v[100:103], v[36:37], off offset:3072
	global_load_dwordx4 v[132:135], v[78:79], off offset:3072
	global_load_dwordx4 v[202:205], v[74:75], off offset:3072
	global_load_dwordx4 v[104:107], v[222:223], off
	global_load_dwordx4 v[136:139], v[224:225], off
	global_load_dwordx4 v[206:209], v[226:227], off
	global_load_dwordx4 v[108:111], v[222:223], off offset:1024
	global_load_dwordx4 v[140:143], v[224:225], off offset:1024
	global_load_dwordx4 v[210:213], v[226:227], off offset:1024
	global_load_dwordx4 v[112:115], v[222:223], off offset:2048
	global_load_dwordx4 v[144:147], v[224:225], off offset:2048
	global_load_dwordx4 v[214:217], v[226:227], off offset:2048
	global_load_dwordx4 v[116:119], v[222:223], off offset:3072
	global_load_dwordx4 v[148:151], v[224:225], off offset:3072
	global_load_dwordx4 v[218:221], v[226:227], off offset:3072
	ds_bpermute_b32 v3, v170, v1
	s_waitcnt lgkmcnt(0)
	v_add_f32_e32 v1, v1, v3
	ds_bpermute_b32 v3, v171, v1
	s_waitcnt lgkmcnt(0)
	v_add_f32_e32 v1, v1, v3
	ds_bpermute_b32 v3, v172, v1
	s_waitcnt lgkmcnt(0)
	v_add_f32_e32 v1, v1, v3
	ds_bpermute_b32 v3, v173, v1
	s_waitcnt lgkmcnt(0)
	v_add_f32_e32 v1, v1, v3
	ds_bpermute_b32 v3, v174, v1
	s_waitcnt lgkmcnt(0)
	v_add_f32_e32 v1, v1, v3
	ds_bpermute_b32 v3, v175, v1
	s_waitcnt lgkmcnt(0)
; __device__ __forceinline__ unsigned pk2(float lo, float hi) { f32x2n v = {lo, hi}; bf16x2n b = __builtin_convertvector(v, bf16x2n); return __builtin_bit_cast(unsigned, b); }
; #define p (kparams())
; __device__ __forceinline__ void norm_rows(const int wv_, KPR p, int l, int src_layer, const float* gvec, int part_shift, int part_scale, bool copy_ctx) {
;     ...
;     const float rstd = rsqrtf(wave_sum(ss) * (1.f / D) + 1e-6f);
;     if (copy_ctx && row_who(row) == 4) { float* xd = xrow_dst(p, row);
; #pragma unroll
;       for (int j = 0; j < 8; ++j) *(f32x4*)(xd + lane * 4 + 256 * j) = v[j]; }
; #pragma unroll
;     for (int j = 0; j < 8; ++j) { const int c = lane * 4 + 256 * j;
;       const f32x4 g = *(const f32x4*)(gvec + c), sh = *(const f32x4*)(mw + part_shift * 2048 + c), sc = *(const f32x4*)(mw + part_scale * 2048 + c);
;       f32x4 o;
; #pragma unroll
;       for (int e = 0; e < 4; ++e) o[e] = v[j][e] * rstd * g[e] * (1.f + sc[e]) + sh[e];
;       u32x2 w; w.x = pk2(o[0], o[1]); w.y = pk2(o[2], o[3]);
;       *(u32x2*)(H + (size_t)row * D + c) = w; }
	v_add_f32_e32 v1, v1, v3
	v_fmamk_f32 v1, v1, 0x3a000000, v152
	v_cmp_gt_f32_e32 vcc, s96, v1
	v_mul_f32_e32 v3, 0x4b800000, v1
	s_nop 0
	v_cndmask_b32_e32 v1, v1, v3, vcc
	v_rsq_f32_e32 v1, v1
	s_nop 0
	v_mul_f32_e32 v3, 0x45800000, v1
	v_cndmask_b32_e32 v64, v1, v3, vcc
	v_pk_mul_f32 v[32:33], v[32:33], v[64:65] op_sel_hi:[1,0]
	v_pk_mul_f32 v[34:35], v[34:35], v[64:65] op_sel_hi:[1,0]
	v_pk_mul_f32 v[28:29], v[28:29], v[64:65] op_sel_hi:[1,0]
	v_pk_mul_f32 v[30:31], v[30:31], v[64:65] op_sel_hi:[1,0]
	v_pk_mul_f32 v[24:25], v[24:25], v[64:65] op_sel_hi:[1,0]
	v_pk_mul_f32 v[26:27], v[26:27], v[64:65] op_sel_hi:[1,0]
	v_pk_mul_f32 v[20:21], v[20:21], v[64:65] op_sel_hi:[1,0]
	v_pk_mul_f32 v[22:23], v[22:23], v[64:65] op_sel_hi:[1,0]
	v_pk_mul_f32 v[16:17], v[16:17], v[64:65] op_sel_hi:[1,0]
	v_pk_mul_f32 v[18:19], v[18:19], v[64:65] op_sel_hi:[1,0]
	v_pk_mul_f32 v[12:13], v[12:13], v[64:65] op_sel_hi:[1,0]
	v_pk_mul_f32 v[14:15], v[14:15], v[64:65] op_sel_hi:[1,0]
	v_pk_mul_f32 v[8:9], v[8:9], v[64:65] op_sel_hi:[1,0]
	v_pk_mul_f32 v[10:11], v[10:11], v[64:65] op_sel_hi:[1,0]
	v_pk_mul_f32 v[4:5], v[4:5], v[64:65] op_sel_hi:[1,0]
	v_pk_mul_f32 v[6:7], v[6:7], v[64:65] op_sel_hi:[1,0]
	v_ashrrev_i32_e32 v1, 31, v0
	v_lshlrev_b64 v[82:83], 12, v[0:1]
	v_lshl_add_u64 v[70:71], v[46:47], 0, v[82:83]
	v_add_u32_e32 v0, s73, v0
	v_cmp_lt_i32_e32 vcc, s38, v0
	s_or_b64 s[18:19], vcc, s[18:19]
	s_waitcnt vmcnt(21)
	v_pk_mul_f32 v[32:33], v[88:89], v[32:33]
	v_pk_mul_f32 v[34:35], v[90:91], v[34:35]
	v_pk_add_f32 v[228:229], v[120:121], 1.0 op_sel_hi:[1,0]
	v_pk_add_f32 v[230:231], v[122:123], 1.0 op_sel_hi:[1,0]
	v_pk_fma_f32 v[32:33], v[228:229], v[32:33], v[190:191]
	v_pk_fma_f32 v[34:35], v[230:231], v[34:35], v[192:193]
	v_cvt_pk_bf16_f32 v32, v32, v33
	v_cvt_pk_bf16_f32 v33, v34, v35
	global_store_dwordx2 v[70:71], v[32:33], off
	s_waitcnt vmcnt(19)
	v_pk_mul_f32 v[28:29], v[92:93], v[28:29]
	v_pk_mul_f32 v[30:31], v[94:95], v[30:31]
	v_pk_add_f32 v[228:229], v[124:125], 1.0 op_sel_hi:[1,0]
	v_pk_add_f32 v[230:231], v[126:127], 1.0 op_sel_hi:[1,0]
	v_pk_fma_f32 v[28:29], v[228:229], v[28:29], v[194:195]
	v_pk_fma_f32 v[30:31], v[230:231], v[30:31], v[196:197]
	v_cvt_pk_bf16_f32 v28, v28, v29
	v_cvt_pk_bf16_f32 v29, v30, v31
	global_store_dwordx2 v[70:71], v[28:29], off offset:512
	s_waitcnt vmcnt(17)
	v_pk_mul_f32 v[24:25], v[96:97], v[24:25]
	v_pk_mul_f32 v[26:27], v[98:99], v[26:27]
	v_pk_add_f32 v[228:229], v[128:129], 1.0 op_sel_hi:[1,0]
	v_pk_add_f32 v[230:231], v[130:131], 1.0 op_sel_hi:[1,0]
	v_pk_fma_f32 v[24:25], v[228:229], v[24:25], v[198:199]
	v_pk_fma_f32 v[26:27], v[230:231], v[26:27], v[200:201]
	v_cvt_pk_bf16_f32 v24, v24, v25
	v_cvt_pk_bf16_f32 v25, v26, v27
	global_store_dwordx2 v[70:71], v[24:25], off offset:1024
	s_waitcnt vmcnt(15)
	v_pk_mul_f32 v[20:21], v[100:101], v[20:21]
	v_pk_mul_f32 v[22:23], v[102:103], v[22:23]
	v_pk_add_f32 v[228:229], v[132:133], 1.0 op_sel_hi:[1,0]
	v_pk_add_f32 v[230:231], v[134:135], 1.0 op_sel_hi:[1,0]
	v_pk_fma_f32 v[20:21], v[228:229], v[20:21], v[202:203]
	v_pk_fma_f32 v[22:23], v[230:231], v[22:23], v[204:205]
	v_cvt_pk_bf16_f32 v20, v20, v21
	v_cvt_pk_bf16_f32 v21, v22, v23
	global_store_dwordx2 v[70:71], v[20:21], off offset:1536
	s_waitcnt vmcnt(13)
	v_pk_mul_f32 v[16:17], v[104:105], v[16:17]
	v_pk_mul_f32 v[18:19], v[106:107], v[18:19]
	v_pk_add_f32 v[228:229], v[136:137], 1.0 op_sel_hi:[1,0]
	v_pk_add_f32 v[230:231], v[138:139], 1.0 op_sel_hi:[1,0]
	v_pk_fma_f32 v[16:17], v[228:229], v[16:17], v[206:207]
	v_pk_fma_f32 v[18:19], v[230:231], v[18:19], v[208:209]
	v_cvt_pk_bf16_f32 v16, v16, v17
	v_cvt_pk_bf16_f32 v17, v18, v19
	global_store_dwordx2 v[70:71], v[16:17], off offset:2048
	s_waitcnt vmcnt(11)
	v_pk_mul_f32 v[12:13], v[108:109], v[12:13]
	v_pk_mul_f32 v[14:15], v[110:111], v[14:15]
	v_pk_add_f32 v[228:229], v[140:141], 1.0 op_sel_hi:[1,0]
	v_pk_add_f32 v[230:231], v[142:143], 1.0 op_sel_hi:[1,0]
	v_pk_fma_f32 v[12:13], v[228:229], v[12:13], v[210:211]
	v_pk_fma_f32 v[14:15], v[230:231], v[14:15], v[212:213]
	v_cvt_pk_bf16_f32 v12, v12, v13
	v_cvt_pk_bf16_f32 v13, v14, v15
	global_store_dwordx2 v[70:71], v[12:13], off offset:2560
	s_waitcnt vmcnt(9)
	v_pk_mul_f32 v[8:9], v[112:113], v[8:9]
	v_pk_mul_f32 v[10:11], v[114:115], v[10:11]
	v_pk_add_f32 v[228:229], v[144:145], 1.0 op_sel_hi:[1,0]
	v_pk_add_f32 v[230:231], v[146:147], 1.0 op_sel_hi:[1,0]
	v_pk_fma_f32 v[8:9], v[228:229], v[8:9], v[214:215]
	v_pk_fma_f32 v[10:11], v[230:231], v[10:11], v[216:217]
	v_cvt_pk_bf16_f32 v8, v8, v9
	v_cvt_pk_bf16_f32 v9, v10, v11
	global_store_dwordx2 v[70:71], v[8:9], off offset:3072
	s_waitcnt vmcnt(7)
	v_pk_mul_f32 v[4:5], v[116:117], v[4:5]
	v_pk_mul_f32 v[6:7], v[118:119], v[6:7]
	v_pk_add_f32 v[228:229], v[148:149], 1.0 op_sel_hi:[1,0]
	v_pk_add_f32 v[230:231], v[150:151], 1.0 op_sel_hi:[1,0]
	v_pk_fma_f32 v[4:5], v[228:229], v[4:5], v[218:219]
	v_pk_fma_f32 v[6:7], v[230:231], v[6:7], v[220:221]
	v_cvt_pk_bf16_f32 v4, v4, v5
	v_cvt_pk_bf16_f32 v5, v6, v7
	global_store_dwordx2 v[70:71], v[4:5], off offset:3584
	s_andn2_b64 exec, exec, s[18:19]
	s_cbranch_execz .LBB0_1108
